# H1 chunk-prep units remapped to the XCD that runs their recurrence; H1->H2 barrier per-XCD too
# speedup vs baseline: 1.0071x; 1.0011x over previous
; #define LAS __attribute__((address_space(3)))
; DI float bf2f(unsigned short h) { return __uint_as_float((unsigned)h << 16); }
; #define H1_RAW(uu, RQ, RF, RV) do { const int c_ = (uu) & 63, h_ = ((uu) >> 6) & 7, b_ = (uu) >> 9; const bf16* p_ = Z2 + (size_t)(b_ * T + 64 * c_ + 16 * rg) * NH2 + h_ * 128 + n; \
;         _Pragma("unroll") for (int r = 0; r < 16; ++r) { RQ[r] = p_[(size_t)r * NH2]; RF[r] = p_[(size_t)r * NH2 + 1024]; RV[r] = p_[(size_t)r * NH2 + 2048]; } } while (0)
; template <bool DRY> DI void hgrn1_phase(LAS unsigned char* L, bf16* Z2, const float* lbraw, int layer, float* DEC, unsigned long long* OI, int G, int bid, int tid) {
;     const int wid = __builtin_amdgcn_readfirstlane(tid >> 6), lane = tid & 63, fr = lane & 15, fq = lane >> 4;
;     const int n = tid & 127, rg = tid >> 7, tt = wid & 3, vh = wid >> 2;
;     LAS float* TOT = (LAS float*)(L + H1_TOT);
;     unsigned short rq[16], rf[16], rv[16];
;     ...
;     if (bid < 2048) H1_RAW(bid, rq, rf, rv);
;     for (int unit = bid; unit < 2048; unit += G) {
;         const int c = unit & 63, h = (unit >> 6) & 7, b = unit >> 9, tok0 = b * T + 64 * c, ch = h * 128 + n;
;         float lbv = 0.f;
;         if (layer > 0) { const float e0 = lbraw[ch], e1 = lbraw[D + ch]; lbv = 1.0f / (1.0f + expf(e0 - e1)); }
;         asm volatile("" : "+v"(rq[0]), "+v"(rq[1]), "+v"(rq[2]), "+v"(rq[3]), "+v"(rq[4]), "+v"(rq[5]), "+v"(rq[6]), "+v"(rq[7]), "+v"(rq[8]), "+v"(rq[9]), "+v"(rq[10]), "+v"(rq[11]), "+v"(rq[12]), "+v"(rq[13]), "+v"(rq[14]), "+v"(rq[15]));
;         asm volatile("" : "+v"(rf[0]), "+v"(rf[1]), "+v"(rf[2]), "+v"(rf[3]), "+v"(rf[4]), "+v"(rf[5]), "+v"(rf[6]), "+v"(rf[7]), "+v"(rf[8]), "+v"(rf[9]), "+v"(rf[10]), "+v"(rf[11]), "+v"(rf[12]), "+v"(rf[13]), "+v"(rf[14]), "+v"(rf[15]));
;         asm volatile("" : "+v"(rv[0]), "+v"(rv[1]), "+v"(rv[2]), "+v"(rv[3]), "+v"(rv[4]), "+v"(rv[5]), "+v"(rv[6]), "+v"(rv[7]), "+v"(rv[8]), "+v"(rv[9]), "+v"(rv[10]), "+v"(rv[11]), "+v"(rv[12]), "+v"(rv[13]), "+v"(rv[14]), "+v"(rv[15]));
;         float q[16], cs[16], kg[16]; unsigned short vr[16];
;         bf16* base = Z2 + (size_t)(tok0 + 16 * rg) * NH2 + ch;
; #pragma unroll
;         for (int r = 0; r < 16; ++r) { q[r] = bf2f(rq[r]); cs[r] = bf2f(rf[r]); vr[r] = rv[r]; }
;         unsigned short nq[16], nf[16], nv[16];
;         { const int nu = unit + G < 2048 ? unit + G : unit; H1_RAW(nu, nq, nf, nv); }
.LBB0_522:
	s_or_b64 exec, exec, s[0:1]
	s_mov_b64 s[24:25], 0
	v_mov_b32_e32 v20, v238
	v_readlane_b32 s0, v252, 0
	s_movk_i32 s2, 32
	s_nop 2
	s_and_b32 s100, s0, 7
	s_lshl_b32 s100, s100, 8
	s_lshr_b32 s0, s0, 3
	s_add_u32 s0, s0, s100
	s_add_u32 s100, s100, 0xff
	s_waitcnt lgkmcnt(0)
	s_barrier
	s_cmpk_gt_i32 s0, 0x7ff
	v_readfirstlane_b32 s1, v20
	s_cbranch_scc1 .LBB0_548
	s_add_u32 s6, s78, s24
	s_addc_u32 s7, s79, s25
	s_add_u32 s4, s6, 0x6400000
	s_addc_u32 s5, s7, 0
	s_lshl_b32 s52, s0, 3
	s_lshl_b32 s53, s0, 6
	v_ashrrev_i32_e32 v31, 7, v20
	s_and_b32 s3, s52, 0xfffff000
	s_and_b32 s8, s53, 0xfc0
	v_lshlrev_b32_e32 v32, 4, v31
	s_or_b32 s3, s3, s8
	s_waitcnt vmcnt(9)
	v_add_u32_e32 v4, s3, v32
	v_ashrrev_i32_e32 v5, 31, v4
	v_lshlrev_b64 v[4:5], 13, v[4:5]
	s_lshl_b32 s27, s0, 2
	v_and_b32_e32 v30, 0x7f, v20
	v_lshl_add_u64 v[4:5], s[4:5], 0, v[4:5]
	s_and_b32 s86, s27, 0x700
	v_lshl_add_u64 v[4:5], v[4:5], 0, s[86:87]
	v_lshlrev_b32_e32 v0, 1, v30
	v_lshl_add_u64 v[22:23], v[4:5], 0, v[0:1]
	s_movk_i32 s3, 0x2000
	v_add_co_u32_e32 v8, vcc, s3, v22
	s_movk_i32 s3, 0x4000
	s_nop 0
	v_addc_co_u32_e32 v9, vcc, 0, v23, vcc
	v_add_co_u32_e32 v14, vcc, s3, v22
	s_movk_i32 s3, 0x6000
	s_nop 0
	v_addc_co_u32_e32 v15, vcc, 0, v23, vcc
	v_add_co_u32_e32 v24, vcc, s3, v22
	s_mov_b32 s3, 0x8000
	s_nop 0
	v_addc_co_u32_e32 v25, vcc, 0, v23, vcc
	global_load_ushort v7, v[22:23], off
	global_load_ushort v5, v[22:23], off offset:2048
	global_load_ushort v6, v[8:9], off offset:-4096
	global_load_ushort v10, v[8:9], off
	s_nop 0
	global_load_ushort v8, v[8:9], off offset:2048
	s_nop 0
	global_load_ushort v9, v[14:15], off offset:-4096
	global_load_ushort v13, v[14:15], off
	global_load_ushort v12, v[14:15], off offset:2048
	global_load_ushort v11, v[24:25], off offset:-4096
	s_nop 0
	global_load_ushort v14, v[24:25], off
	global_load_ushort v15, v[24:25], off offset:2048
	v_add_co_u32_e32 v24, vcc, s3, v22
	s_mov_b32 s3, 0xa000
	s_nop 0
	v_addc_co_u32_e32 v25, vcc, 0, v23, vcc
	global_load_ushort v28, v[24:25], off offset:-4096
	global_load_ushort v19, v[24:25], off
	global_load_ushort v16, v[24:25], off offset:2048
	v_add_co_u32_e32 v24, vcc, s3, v22
	s_mov_b32 s3, 0xc000
	s_nop 0
	v_addc_co_u32_e32 v25, vcc, 0, v23, vcc
	global_load_ushort v36, v[24:25], off offset:-4096
	global_load_ushort v37, v[24:25], off
	global_load_ushort v38, v[24:25], off offset:2048
	v_add_co_u32_e32 v24, vcc, s3, v22
	s_mov_b32 s3, 0xe000
	s_nop 0
	v_addc_co_u32_e32 v25, vcc, 0, v23, vcc
	global_load_ushort v47, v[24:25], off offset:-4096
	global_load_ushort v41, v[24:25], off
	global_load_ushort v48, v[24:25], off offset:2048
	v_add_co_u32_e32 v24, vcc, s3, v22
	s_mov_b32 s3, 0x10000
	s_nop 0
	v_addc_co_u32_e32 v25, vcc, 0, v23, vcc
	global_load_ushort v49, v[24:25], off offset:-4096
	global_load_ushort v42, v[24:25], off
	global_load_ushort v50, v[24:25], off offset:2048
	v_add_co_u32_e32 v24, vcc, s3, v22
	s_mov_b32 s3, 0x12000
	s_nop 0
	v_addc_co_u32_e32 v25, vcc, 0, v23, vcc
	global_load_ushort v51, v[24:25], off offset:-4096
	global_load_ushort v43, v[24:25], off
	global_load_ushort v52, v[24:25], off offset:2048
	v_add_co_u32_e32 v24, vcc, s3, v22
	s_mov_b32 s3, 0x14000
	s_nop 0
	v_addc_co_u32_e32 v25, vcc, 0, v23, vcc
	global_load_ushort v53, v[24:25], off offset:-4096
	global_load_ushort v54, v[24:25], off
	global_load_ushort v55, v[24:25], off offset:2048
	v_add_co_u32_e32 v24, vcc, s3, v22
	s_mov_b32 s3, 0x16000
	s_nop 0
	v_addc_co_u32_e32 v25, vcc, 0, v23, vcc
	global_load_ushort v56, v[24:25], off offset:-4096
	global_load_ushort v57, v[24:25], off
	global_load_ushort v58, v[24:25], off offset:2048
	v_add_co_u32_e32 v24, vcc, s3, v22
	s_mov_b32 s3, 0x18000
	s_nop 0
	v_addc_co_u32_e32 v25, vcc, 0, v23, vcc
	global_load_ushort v59, v[24:25], off offset:-4096
	global_load_ushort v60, v[24:25], off
	global_load_ushort v63, v[24:25], off offset:2048
	v_add_co_u32_e32 v24, vcc, s3, v22
	s_mov_b32 s3, 0x1a000
	s_nop 0
	v_addc_co_u32_e32 v25, vcc, 0, v23, vcc
	global_load_ushort v64, v[24:25], off offset:-4096
	global_load_ushort v61, v[24:25], off
	global_load_ushort v65, v[24:25], off offset:2048
	v_add_co_u32_e32 v24, vcc, s3, v22
	s_mov_b32 s3, 0x1c000
	s_nop 0
	v_addc_co_u32_e32 v25, vcc, 0, v23, vcc
	global_load_ushort v66, v[24:25], off offset:-4096
	global_load_ushort v62, v[24:25], off
	global_load_ushort v67, v[24:25], off offset:2048
	v_add_co_u32_e32 v24, vcc, s3, v22
	s_mov_b32 s3, 0x1e000
	s_nop 0
	v_addc_co_u32_e32 v25, vcc, 0, v23, vcc
	global_load_ushort v68, v[24:25], off offset:-4096
	global_load_ushort v69, v[24:25], off
	global_load_ushort v70, v[24:25], off offset:2048
	v_add_co_u32_e32 v24, vcc, s3, v22
	s_mov_b32 s3, 0x1f000
	s_nop 0
	v_addc_co_u32_e32 v25, vcc, 0, v23, vcc
	v_add_co_u32_e32 v22, vcc, s3, v22
	global_load_ushort v71, v[24:25], off offset:-4096
	global_load_ushort v72, v[24:25], off
	global_load_ushort v73, v[24:25], off offset:2048
	v_addc_co_u32_e32 v23, vcc, 0, v23, vcc
	global_load_ushort v74, v[22:23], off
	v_lshlrev_b32_e32 v4, 2, v30
	s_movk_i32 s3, 0x80
	v_add_u32_e32 v45, 0, v4
	v_cmp_gt_u32_e64 s[36:37], s3, v20
	s_movk_i32 s3, 0x7f
	s_bfe_u32 s26, s1, 0x20006
	v_and_b32_e32 v3, 15, v20
	v_cmp_lt_u32_e64 s[38:39], s3, v20
	v_sub_u32_e32 v22, v45, v0
	v_lshlrev_b32_e32 v0, 6, v20
	s_movk_i32 s3, 0x8e
	s_ashr_i32 s1, s1, 6
	v_and_b32_e32 v17, 63, v20
	s_lshl_b32 s54, s0, 1
	v_and_b32_e32 v2, 64, v0
	v_mad_u32_u24 v23, v30, s3, v22
	v_lshl_or_b32 v0, s26, 4, v3
	s_movk_i32 s3, 0x110
	s_and_b32 s20, s1, -4
	v_mad_u32_u24 v26, v0, s3, 0
	v_lshlrev_b32_e32 v0, 3, v17
	s_cmp_eq_u32 s26, 0
	v_bfe_u32 v18, v20, 4, 2
	v_lshl_add_u32 v44, v20, 2, 0
	v_bfe_u32 v46, v20, 1, 6
	v_and_b32_e32 v27, 48, v20
	v_lshl_add_u64 v[20:21], s[6:7], 0, v[0:1]
	s_mov_b64 s[6:7], 0xf400000
	s_cselect_b64 s[40:41], -1, 0
	s_cmp_lg_u32 s26, 0
	v_lshl_add_u64 v[34:35], v[20:21], 0, s[6:7]
	s_cselect_b64 s[6:7], -1, 0
	s_cmp_eq_u32 s26, 1
	v_lshlrev_b32_e32 v29, 2, v18
	s_cselect_b64 s[8:9], -1, 0
	s_cmp_gt_u32 s26, 1
	v_or_b32_e32 v0, 2, v29
	s_cselect_b64 s[10:11], -1, 0
	s_cmp_eq_u32 s26, 2
	s_movk_i32 s3, 0x1100
	v_cmp_gt_u32_e64 s[46:47], v0, v3
	v_or_b32_e32 v0, 3, v29
	s_cselect_b64 s[12:13], -1, 0
	s_cmp_eq_u32 s26, 3
	v_mul_lo_u32 v76, v31, s3
	v_cmp_gt_u32_e64 s[48:49], v0, v3
	s_cselect_b64 s[14:15], -1, 0
	v_lshl_or_b32 v0, s20, 4, v3
	s_movk_i32 s3, 0x90
	s_ashr_i32 s21, s20, 31
	s_or_b32 s18, s20, 1
	v_mul_lo_u32 v78, v0, s3
	s_lshl_b64 s[16:17], s[20:21], 9
	v_lshl_or_b32 v0, s18, 4, v3
	s_or_b32 s20, s20, 2
	s_or_b32 s22, s1, 3
	s_mov_b32 s1, 0x5040100
	v_lshl_add_u32 v75, v18, 3, 0
	v_cmp_gt_u32_e64 s[42:43], v29, v3
	v_cmp_lt_u32_e64 s[44:45], v29, v3
	v_mul_lo_u32 v79, v0, s3
	s_ashr_i32 s19, s18, 31
	v_lshl_or_b32 v0, s20, 4, v3
	s_ashr_i32 s21, s20, 31
	s_ashr_i32 s23, s22, 31
	s_waitcnt vmcnt(44)
; DI float bf2f(unsigned short h) { return __uint_as_float((unsigned)h << 16); }
; #define H1_RAW(uu, RQ, RF, RV) do { const int c_ = (uu) & 63, h_ = ((uu) >> 6) & 7, b_ = (uu) >> 9; const bf16* p_ = Z2 + (size_t)(b_ * T + 64 * c_ + 16 * rg) * NH2 + h_ * 128 + n; \
;         _Pragma("unroll") for (int r = 0; r < 16; ++r) { RQ[r] = p_[(size_t)r * NH2]; RF[r] = p_[(size_t)r * NH2 + 1024]; RV[r] = p_[(size_t)r * NH2 + 2048]; } } while (0)
; template <bool DRY> DI void hgrn1_phase(LAS unsigned char* L, bf16* Z2, const float* lbraw, int layer, float* DEC, unsigned long long* OI, int G, int bid, int tid) {
;     ...
;     if (bid < 2048) H1_RAW(bid, rq, rf, rv);
;     for (int unit = bid; unit < 2048; unit += G) {
;         const int c = unit & 63, h = (unit >> 6) & 7, b = unit >> 9, tok0 = b * T + 64 * c, ch = h * 128 + n;
;         float lbv = 0.f;
;         if (layer > 0) { const float e0 = lbraw[ch], e1 = lbraw[D + ch]; lbv = 1.0f / (1.0f + expf(e0 - e1)); }
;         asm volatile("" : "+v"(rq[0]), "+v"(rq[1]), "+v"(rq[2]), "+v"(rq[3]), "+v"(rq[4]), "+v"(rq[5]), "+v"(rq[6]), "+v"(rq[7]), "+v"(rq[8]), "+v"(rq[9]), "+v"(rq[10]), "+v"(rq[11]), "+v"(rq[12]), "+v"(rq[13]), "+v"(rq[14]), "+v"(rq[15]));
;         asm volatile("" : "+v"(rf[0]), "+v"(rf[1]), "+v"(rf[2]), "+v"(rf[3]), "+v"(rf[4]), "+v"(rf[5]), "+v"(rf[6]), "+v"(rf[7]), "+v"(rf[8]), "+v"(rf[9]), "+v"(rf[10]), "+v"(rf[11]), "+v"(rf[12]), "+v"(rf[13]), "+v"(rf[14]), "+v"(rf[15]));
;         asm volatile("" : "+v"(rv[0]), "+v"(rv[1]), "+v"(rv[2]), "+v"(rv[3]), "+v"(rv[4]), "+v"(rv[5]), "+v"(rv[6]), "+v"(rv[7]), "+v"(rv[8]), "+v"(rv[9]), "+v"(rv[10]), "+v"(rv[11]), "+v"(rv[12]), "+v"(rv[13]), "+v"(rv[14]), "+v"(rv[15]));
;         float q[16], cs[16], kg[16]; unsigned short vr[16];
;         bf16* base = Z2 + (size_t)(tok0 + 16 * rg) * NH2 + ch;
; #pragma unroll
;         for (int r = 0; r < 16; ++r) { q[r] = bf2f(rq[r]); cs[r] = bf2f(rf[r]); vr[r] = rv[r]; }
	v_perm_b32 v29, v10, v7, s1
	s_waitcnt vmcnt(38)
	v_perm_b32 v39, v14, v13, s1
	s_waitcnt vmcnt(32)
	v_perm_b32 v40, v37, v19, s1
	s_waitcnt vmcnt(26)
	v_perm_b32 v41, v42, v41, s1
	s_waitcnt vmcnt(20)
	v_perm_b32 v42, v54, v43, s1
	s_waitcnt vmcnt(14)
	v_perm_b32 v43, v60, v57, s1
	s_waitcnt vmcnt(8)
	v_perm_b32 v61, v62, v61, s1
	v_perm_b32 v14, v8, v5, s1
	v_perm_b32 v15, v15, v12, s1
	v_perm_b32 v16, v38, v16, s1
	s_waitcnt vmcnt(2)
	v_perm_b32 v62, v72, v69, s1
	v_perm_b32 v17, v50, v48, s1
	v_perm_b32 v18, v55, v52, s1
	v_perm_b32 v19, v63, v58, s1
	v_perm_b32 v20, v67, v65, s1
	s_waitcnt vmcnt(1)
	v_perm_b32 v21, v73, v70, s1
	v_perm_b32 v6, v9, v6, s1
	v_perm_b32 v7, v28, v11, s1
	v_perm_b32 v8, v47, v36, s1
	v_perm_b32 v9, v51, v49, s1
	v_perm_b32 v10, v56, v53, s1
	v_perm_b32 v11, v64, v59, s1
	v_perm_b32 v12, v68, v66, s1
	s_waitcnt vmcnt(0)
	v_perm_b32 v13, v74, v71, s1
	s_ashr_i32 s1, s0, 31
	s_lshl_b64 s[18:19], s[18:19], 9
	v_mul_lo_u32 v80, v0, s3
	s_lshl_b64 s[20:21], s[20:21], 9
	v_lshl_or_b32 v0, s22, 4, v3
	s_lshl_b64 s[22:23], s[22:23], 9
	s_lshl_b64 s[28:29], s[0:1], 9
	s_add_u32 s1, s24, s28
	v_mul_u32_u24_e32 v77, 0x110, v3
	v_mul_lo_u32 v3, v0, s3
	s_addc_u32 s3, s25, s29
	v_readlane_b32 s24, v254, 21
	s_add_u32 s24, s24, s1
	v_readlane_b32 s1, v254, 22
	v_lshlrev_b32_e32 v25, 5, v31
	v_add_u32_e32 v24, 0, v27
	v_mov_b32_e32 v5, v1
	s_addc_u32 s25, s1, s3
	s_ashr_i32 s3, s2, 31
	v_ashrrev_i32_e32 v33, 31, v32
	v_lshl_add_u64 v[36:37], s[24:25], 0, v[4:5]
	s_lshl_b64 s[24:25], s[2:3], 9
	s_or_b32 s26, s27, s26
	s_lshl_b32 s3, s2, 2
	s_lshl_b32 s55, s2, 1
	s_lshl_b32 s56, s2, 6
	s_lshl_b32 s57, s2, 3
	v_lshlrev_b32_e32 v0, 1, v30
	v_add_u32_e32 v47, v22, v76
	v_lshlrev_b32_e32 v38, 1, v2
	v_add_u32_e32 v48, v23, v25
	v_add_u32_e32 v49, v26, v27
	v_add_u32_e32 v50, v75, v78
	v_add_u32_e32 v51, v75, v79
	v_add_u32_e32 v52, v75, v80
	v_add_u32_e32 v53, v75, v3
	v_add_u32_e32 v54, v24, v77
	s_branch .LBB0_525

; DI float bf2f(unsigned short h) { return __uint_as_float((unsigned)h << 16); }
; #define H1_RAW(uu, RQ, RF, RV) do { const int c_ = (uu) & 63, h_ = ((uu) >> 6) & 7, b_ = (uu) >> 9; const bf16* p_ = Z2 + (size_t)(b_ * T + 64 * c_ + 16 * rg) * NH2 + h_ * 128 + n; \
;         _Pragma("unroll") for (int r = 0; r < 16; ++r) { RQ[r] = p_[(size_t)r * NH2]; RF[r] = p_[(size_t)r * NH2 + 1024]; RV[r] = p_[(size_t)r * NH2 + 2048]; } } while (0)
; template <bool DRY> DI void hgrn1_phase(LAS unsigned char* L, bf16* Z2, const float* lbraw, int layer, float* DEC, unsigned long long* OI, int G, int bid, int tid) {
;     ...
;     if (bid < 2048) H1_RAW(bid, rq, rf, rv);
;     for (int unit = bid; unit < 2048; unit += G) {
;         const int c = unit & 63, h = (unit >> 6) & 7, b = unit >> 9, tok0 = b * T + 64 * c, ch = h * 128 + n;
;         float lbv = 0.f;
;         if (layer > 0) { const float e0 = lbraw[ch], e1 = lbraw[D + ch]; lbv = 1.0f / (1.0f + expf(e0 - e1)); }
;         asm volatile("" : "+v"(rq[0]), "+v"(rq[1]), "+v"(rq[2]), "+v"(rq[3]), "+v"(rq[4]), "+v"(rq[5]), "+v"(rq[6]), "+v"(rq[7]), "+v"(rq[8]), "+v"(rq[9]), "+v"(rq[10]), "+v"(rq[11]), "+v"(rq[12]), "+v"(rq[13]), "+v"(rq[14]), "+v"(rq[15]));
;         asm volatile("" : "+v"(rf[0]), "+v"(rf[1]), "+v"(rf[2]), "+v"(rf[3]), "+v"(rf[4]), "+v"(rf[5]), "+v"(rf[6]), "+v"(rf[7]), "+v"(rf[8]), "+v"(rf[9]), "+v"(rf[10]), "+v"(rf[11]), "+v"(rf[12]), "+v"(rf[13]), "+v"(rf[14]), "+v"(rf[15]));
;         asm volatile("" : "+v"(rv[0]), "+v"(rv[1]), "+v"(rv[2]), "+v"(rv[3]), "+v"(rv[4]), "+v"(rv[5]), "+v"(rv[6]), "+v"(rv[7]), "+v"(rv[8]), "+v"(rv[9]), "+v"(rv[10]), "+v"(rv[11]), "+v"(rv[12]), "+v"(rv[13]), "+v"(rv[14]), "+v"(rv[15]));
;         float q[16], cs[16], kg[16]; unsigned short vr[16];
;         bf16* base = Z2 + (size_t)(tok0 + 16 * rg) * NH2 + ch;
; #pragma unroll
;         for (int r = 0; r < 16; ++r) { q[r] = bf2f(rq[r]); cs[r] = bf2f(rf[r]); vr[r] = rv[r]; }
;         unsigned short nq[16], nf[16], nv[16];
;         { const int nu = unit + G < 2048 ? unit + G : unit; H1_RAW(nu, nq, nf, nv); }
.LBB0_527:
	s_add_i32 s58, s0, s2
	s_cmp_gt_i32 s58, s100
	s_cselect_b64 s[28:29], -1, 0
	s_cmp_le_i32 s58, s100
	s_cselect_b32 s0, s58, s0
	s_lshl_b32 s1, s0, 3
	s_lshl_b32 s30, s0, 6
	s_and_b32 s1, s1, 0xfffff000
	s_and_b32 s30, s30, 0xfc0
	s_or_b32 s1, s1, s30
	v_lshrrev_b32_e32 v136, 16, v6
	v_and_b32_e32 v140, 0xffff, v6
	v_add_u32_e32 v6, s1, v32
	v_lshrrev_b32_e32 v132, 16, v7
	v_and_b32_e32 v137, 0xffff, v7
	v_ashrrev_i32_e32 v7, 31, v6
	v_lshlrev_b64 v[6:7], 13, v[6:7]
	s_lshl_b32 s0, s0, 2
	v_lshl_add_u64 v[6:7], s[4:5], 0, v[6:7]
	s_and_b32 s86, s0, 0x700
	v_lshl_add_u64 v[6:7], v[6:7], 0, s[86:87]
	v_lshrrev_b32_e32 v130, 16, v8
	v_lshrrev_b32_e32 v127, 16, v9
	v_and_b32_e32 v133, 0xffff, v8
	v_and_b32_e32 v129, 0xffff, v9
	v_lshl_add_u64 v[8:9], v[6:7], 0, v[0:1]
	s_movk_i32 s0, 0x2000
	v_lshrrev_b32_e32 v138, 16, v10
	v_and_b32_e32 v141, 0xffff, v10
	v_add_co_u32_e32 v10, vcc, s0, v8
	v_lshrrev_b32_e32 v134, 16, v11
	v_and_b32_e32 v139, 0xffff, v11
	v_addc_co_u32_e32 v11, vcc, 0, v9, vcc
	s_movk_i32 s0, 0x4000
	v_lshrrev_b32_e32 v131, 16, v12
	v_and_b32_e32 v135, 0xffff, v12
	v_add_co_u32_e32 v12, vcc, s0, v8
	v_lshrrev_b32_e32 v126, 16, v13
	v_and_b32_e32 v128, 0xffff, v13
	v_addc_co_u32_e32 v13, vcc, 0, v9, vcc
	s_movk_i32 s0, 0x6000
	v_lshrrev_b32_e32 v120, 16, v29
	v_lshrrev_b32_e32 v117, 16, v39
	v_lshrrev_b32_e32 v114, 16, v40
	v_lshrrev_b32_e32 v112, 16, v41
	v_lshrrev_b32_e32 v109, 16, v42
	v_lshrrev_b32_e32 v107, 16, v43
	v_lshrrev_b32_e32 v23, 16, v61
	v_lshrrev_b32_e32 v22, 16, v62
	v_and_b32_e32 v146, 0xffff, v29
	v_and_b32_e32 v145, 0xffff, v39
	v_and_b32_e32 v144, 0xffff, v40
	v_and_b32_e32 v125, 0xffff, v41
	v_and_b32_e32 v122, 0xffff, v42
	v_and_b32_e32 v143, 0xffff, v43
	v_and_b32_e32 v142, 0xffff, v61
	v_and_b32_e32 v39, 0xffff, v62
	v_lshrrev_b32_e32 v24, 16, v14
	v_lshrrev_b32_e32 v25, 16, v15
	v_lshrrev_b32_e32 v26, 16, v16
	v_lshrrev_b32_e32 v27, 16, v17
	v_lshrrev_b32_e32 v55, 16, v18
	v_lshrrev_b32_e32 v56, 16, v19
	v_lshrrev_b32_e32 v57, 16, v20
	v_lshrrev_b32_e32 v58, 16, v21
	v_and_b32_e32 v2, 0xffff, v14
	v_and_b32_e32 v14, 0xffff, v15
	v_and_b32_e32 v15, 0xffff, v16
	v_and_b32_e32 v16, 0xffff, v17
	v_and_b32_e32 v17, 0xffff, v18
	v_and_b32_e32 v18, 0xffff, v19
	v_and_b32_e32 v19, 0xffff, v20
	v_and_b32_e32 v59, 0xffff, v21
	v_add_co_u32_e32 v6, vcc, s0, v8
	s_mov_b32 s0, 0x8000
	s_nop 0
	v_addc_co_u32_e32 v7, vcc, 0, v9, vcc
	v_lshlrev_b32_e32 v28, 16, v14
	v_add_co_u32_e32 v14, vcc, s0, v8
	v_lshlrev_b32_e32 v40, 16, v15
	s_nop 0
	v_addc_co_u32_e32 v15, vcc, 0, v9, vcc
	s_mov_b32 s0, 0xa000
	v_lshlrev_b32_e32 v21, 16, v24
	v_add_co_u32_e32 v24, vcc, s0, v8
	v_lshlrev_b32_e32 v29, 16, v25
	s_nop 0
	v_addc_co_u32_e32 v25, vcc, 0, v9, vcc
	s_mov_b32 s0, 0xc000
	v_lshlrev_b32_e32 v42, 16, v16
	v_lshlrev_b32_e32 v103, 16, v17
	v_lshlrev_b32_e32 v104, 16, v55
	v_lshlrev_b32_e32 v105, 16, v18
	v_lshlrev_b32_e32 v20, 16, v56
	v_lshlrev_b32_e32 v18, 16, v57
	v_lshlrev_b32_e32 v17, 16, v59
	v_lshlrev_b32_e32 v16, 16, v58
	global_load_ushort v57, v[12:13], off offset:2048
	global_load_ushort v55, v[6:7], off offset:-4096
	global_load_ushort v61, v[6:7], off
	global_load_ushort v59, v[6:7], off offset:2048
	global_load_ushort v56, v[14:15], off offset:-4096
	global_load_ushort v62, v[14:15], off
	global_load_ushort v60, v[14:15], off offset:2048
	global_load_ushort v58, v[24:25], off offset:-4096
	v_add_co_u32_e32 v6, vcc, s0, v8
	s_mov_b32 s0, 0xe000
	s_nop 0
	v_addc_co_u32_e32 v7, vcc, 0, v9, vcc
	v_add_co_u32_e32 v14, vcc, s0, v8
	s_mov_b32 s0, 0x10000
	s_nop 0
	v_addc_co_u32_e32 v15, vcc, 0, v9, vcc
	global_load_ushort v67, v[24:25], off
	global_load_ushort v65, v[24:25], off offset:2048
	global_load_ushort v63, v[6:7], off offset:-4096
	global_load_ushort v69, v[6:7], off
	global_load_ushort v66, v[6:7], off offset:2048
	global_load_ushort v64, v[14:15], off offset:-4096
	global_load_ushort v70, v[14:15], off
	global_load_ushort v68, v[14:15], off offset:2048
	v_add_co_u32_e32 v6, vcc, s0, v8
	s_mov_b32 s0, 0x12000
	s_nop 0
	v_addc_co_u32_e32 v7, vcc, 0, v9, vcc
	v_add_co_u32_e32 v14, vcc, s0, v8
	s_mov_b32 s0, 0x14000
	s_nop 0
	v_addc_co_u32_e32 v15, vcc, 0, v9, vcc
	v_add_co_u32_e32 v24, vcc, s0, v8
	s_mov_b32 s0, 0x16000
	s_nop 0
	v_addc_co_u32_e32 v25, vcc, 0, v9, vcc
	global_load_ushort v71, v[6:7], off offset:-4096
	global_load_ushort v76, v[6:7], off
	global_load_ushort v74, v[6:7], off offset:2048
	global_load_ushort v72, v[14:15], off offset:-4096
	global_load_ushort v77, v[14:15], off
	global_load_ushort v75, v[14:15], off offset:2048
	global_load_ushort v73, v[24:25], off offset:-4096
	global_load_ushort v78, v[24:25], off
	v_add_co_u32_e32 v6, vcc, s0, v8
	s_mov_b32 s0, 0x18000
	s_nop 0
	v_addc_co_u32_e32 v7, vcc, 0, v9, vcc
	v_lshlrev_b32_e32 v2, 16, v2
	v_add_co_u32_e32 v14, vcc, s0, v8
	s_mov_b32 s0, 0x1a000
	s_nop 0
	v_addc_co_u32_e32 v15, vcc, 0, v9, vcc
	v_mul_f32_e32 v2, 0xbfb8aa3b, v2
	v_lshlrev_b32_e32 v41, 16, v26
	v_add_co_u32_e32 v26, vcc, s0, v8
	v_exp_f32_e32 v2, v2
	v_lshlrev_b32_e32 v43, 16, v27
	v_addc_co_u32_e32 v27, vcc, 0, v9, vcc
	s_mov_b32 s0, 0x1c000
	global_load_ushort v81, v[24:25], off offset:2048
	global_load_ushort v79, v[6:7], off offset:-4096
	global_load_ushort v85, v[6:7], off
	global_load_ushort v83, v[6:7], off offset:2048
	global_load_ushort v80, v[14:15], off offset:-4096
	global_load_ushort v86, v[14:15], off
	global_load_ushort v84, v[14:15], off offset:2048
	global_load_ushort v82, v[26:27], off offset:-4096
	v_add_co_u32_e32 v6, vcc, s0, v8
	s_mov_b32 s0, 0x1e000
	s_nop 0
	v_addc_co_u32_e32 v7, vcc, 0, v9, vcc
	v_add_co_u32_e32 v14, vcc, s0, v8
; template <bool DRY> DI void hgrn1_phase(LAS unsigned char* L, bf16* Z2, const float* lbraw, int layer, float* DEC, unsigned long long* OI, int G, int bid, int tid) {
;     ...
;         float run = 0.f;
; #pragma unroll
;         for (int r = 0; r < 16; ++r) { const float fl = cs[r]; const float sg = __builtin_amdgcn_rcpf(1.0f + __expf(-fl)); const float f = lbv + (1.0f - lbv) * sg;
;             kg[r] = (1.0f - lbv) * (1.0f - sg); run += __logf(f); cs[r] = run; }
	v_add_f32_e32 v2, 1.0, v2
	s_nop 0
	v_addc_co_u32_e32 v15, vcc, 0, v9, vcc
	global_load_ushort v92, v[26:27], off
	global_load_ushort v89, v[26:27], off offset:2048
	global_load_ushort v87, v[6:7], off offset:-4096
	global_load_ushort v93, v[6:7], off
	global_load_ushort v90, v[6:7], off offset:2048
	global_load_ushort v88, v[14:15], off offset:-4096
	global_load_ushort v94, v[14:15], off
	global_load_ushort v91, v[14:15], off offset:2048
	v_rcp_f32_e32 v6, v2
	s_mov_b32 s0, 0x1f000
	v_add_co_u32_e32 v14, vcc, s0, v8
	v_sub_f32_e32 v2, 1.0, v5
	s_nop 0
	v_addc_co_u32_e32 v15, vcc, 0, v9, vcc
	v_fma_f32 v7, v2, v6, v5
	s_mov_b32 s30, 0x800000
	v_cmp_gt_f32_e32 vcc, s30, v7
	global_load_ushort v100, v[8:9], off
	global_load_ushort v98, v[8:9], off offset:2048
	global_load_ushort v96, v[10:11], off offset:-4096
	global_load_ushort v101, v[10:11], off
	global_load_ushort v99, v[10:11], off offset:2048
	global_load_ushort v97, v[12:13], off offset:-4096
	global_load_ushort v102, v[12:13], off
	global_load_ushort v95, v[14:15], off
	v_cndmask_b32_e64 v24, 0, 32, vcc
	v_ldexp_f32 v7, v7, v24
	v_log_f32_e32 v24, v7
	v_mul_f32_e32 v7, 0xbfb8aa3b, v21
	v_exp_f32_e32 v7, v7
	s_mov_b32 s31, 0x3f317217
	v_mul_f32_e32 v8, 0x3f317217, v24
	v_fma_f32 v8, v24, s31, -v8
	v_add_f32_e32 v7, 1.0, v7
	v_rcp_f32_e32 v7, v7
	v_fmac_f32_e32 v8, 0x3377d1cf, v24
	s_mov_b32 s34, 0x7f800000
	v_fmac_f32_e32 v8, 0x3f317217, v24
	v_cmp_lt_f32_e64 s[0:1], |v24|, s34
	v_fma_f32 v9, v2, v7, v5
	v_mul_f32_e32 v20, 0xbfb8aa3b, v20
	v_cndmask_b32_e64 v8, v24, v8, s[0:1]
	v_cmp_gt_f32_e64 s[0:1], s30, v9
	v_exp_f32_e32 v20, v20
	v_lshlrev_b32_e32 v19, 16, v19
	v_cndmask_b32_e64 v10, 0, 32, s[0:1]
	v_ldexp_f32 v9, v9, v10
	v_cndmask_b32_e32 v10, 0, v243, vcc
	v_log_f32_e32 v9, v9
	v_sub_f32_e32 v8, v8, v10
	v_mul_f32_e32 v10, 0xbfb8aa3b, v28
	v_exp_f32_e32 v10, v10
	v_add_f32_e32 v124, 0, v8
	v_mul_f32_e32 v8, 0x3f317217, v9
	v_fma_f32 v11, v9, s31, -v8
	v_add_f32_e32 v8, 1.0, v10
	v_rcp_f32_e32 v8, v8
	v_fmac_f32_e32 v11, 0x3377d1cf, v9
	v_fmac_f32_e32 v11, 0x3f317217, v9
	v_cmp_lt_f32_e64 vcc, |v9|, s34
	v_cndmask_b32_e64 v10, 0, v243, s[0:1]
	v_add_f32_e32 v20, 1.0, v20
	v_cndmask_b32_e32 v9, v9, v11, vcc
	v_sub_f32_e32 v9, v9, v10
	v_fma_f32 v10, v2, v8, v5
	v_cmp_gt_f32_e32 vcc, s30, v10
	v_add_f32_e32 v123, v9, v124
	v_mul_f32_e32 v9, 0xbfb8aa3b, v29
	v_cndmask_b32_e64 v11, 0, 32, vcc
	v_ldexp_f32 v10, v10, v11
	v_exp_f32_e32 v9, v9
	v_log_f32_e32 v10, v10
	v_mul_f32_e32 v19, 0xbfb8aa3b, v19
	v_exp_f32_e32 v19, v19
	v_add_f32_e32 v9, 1.0, v9
	v_mul_f32_e32 v11, 0x3f317217, v10
	v_rcp_f32_e32 v9, v9
	v_fma_f32 v11, v10, s31, -v11
	v_fmac_f32_e32 v11, 0x3377d1cf, v10
	v_fmac_f32_e32 v11, 0x3f317217, v10
	v_cmp_lt_f32_e64 s[0:1], |v10|, s34
	v_add_f32_e32 v19, 1.0, v19
	v_mul_f32_e32 v18, 0xbfb8aa3b, v18
	v_cndmask_b32_e64 v10, v10, v11, s[0:1]
	v_fma_f32 v11, v2, v9, v5
	v_cmp_gt_f32_e64 s[0:1], s30, v11
	v_exp_f32_e32 v18, v18
	v_mul_f32_e32 v17, 0xbfb8aa3b, v17
	v_cndmask_b32_e64 v12, 0, 32, s[0:1]
	v_ldexp_f32 v11, v11, v12
	v_cndmask_b32_e32 v12, 0, v243, vcc
	v_log_f32_e32 v11, v11
	v_sub_f32_e32 v10, v10, v12
	v_mul_f32_e32 v12, 0xbfb8aa3b, v40
	v_exp_f32_e32 v12, v12
	v_add_f32_e32 v121, v10, v123
	v_mul_f32_e32 v10, 0x3f317217, v11
	v_fma_f32 v13, v11, s31, -v10
	v_add_f32_e32 v10, 1.0, v12
	v_rcp_f32_e32 v10, v10
	v_fmac_f32_e32 v13, 0x3377d1cf, v11
	v_fmac_f32_e32 v13, 0x3f317217, v11
	v_cmp_lt_f32_e64 vcc, |v11|, s34
	v_cndmask_b32_e64 v12, 0, v243, s[0:1]
	v_add_f32_e32 v18, 1.0, v18
	v_cndmask_b32_e32 v11, v11, v13, vcc
	v_sub_f32_e32 v11, v11, v12
	v_fma_f32 v12, v2, v10, v5
	v_cmp_gt_f32_e32 vcc, s30, v12
	v_add_f32_e32 v119, v11, v121
	v_mul_f32_e32 v11, 0xbfb8aa3b, v41
	v_cndmask_b32_e64 v13, 0, 32, vcc
	v_ldexp_f32 v12, v12, v13
	v_exp_f32_e32 v11, v11
	v_log_f32_e32 v12, v12
	v_rcp_f32_e32 v27, v18
	v_exp_f32_e32 v17, v17
	v_add_f32_e32 v11, 1.0, v11
	v_mul_f32_e32 v13, 0x3f317217, v12
	v_rcp_f32_e32 v11, v11
	v_fma_f32 v13, v12, s31, -v13
	v_fmac_f32_e32 v13, 0x3377d1cf, v12
	v_fmac_f32_e32 v13, 0x3f317217, v12
	v_cmp_lt_f32_e64 s[0:1], |v12|, s34
	v_add_f32_e32 v17, 1.0, v17
	v_rcp_f32_e32 v28, v17
	v_cndmask_b32_e64 v12, v12, v13, s[0:1]
	v_fma_f32 v13, v2, v11, v5
	v_cmp_gt_f32_e64 s[0:1], s30, v13
	v_mul_f32_e32 v16, 0xbfb8aa3b, v16
	v_exp_f32_e32 v16, v16
	v_cndmask_b32_e64 v14, 0, 32, s[0:1]
	v_ldexp_f32 v13, v13, v14
	v_cndmask_b32_e32 v14, 0, v243, vcc
	v_log_f32_e32 v13, v13
	v_sub_f32_e32 v12, v12, v14
	v_mul_f32_e32 v14, 0xbfb8aa3b, v42
	v_exp_f32_e32 v14, v14
	v_add_f32_e32 v118, v12, v119
	v_mul_f32_e32 v12, 0x3f317217, v13
	v_fma_f32 v15, v13, s31, -v12
	v_add_f32_e32 v12, 1.0, v14
	v_rcp_f32_e32 v12, v12
	v_fmac_f32_e32 v15, 0x3377d1cf, v13
	v_fmac_f32_e32 v15, 0x3f317217, v13
	v_cmp_lt_f32_e64 vcc, |v13|, s34
	v_cndmask_b32_e64 v14, 0, v243, s[0:1]
	v_add_f32_e32 v16, 1.0, v16
	v_cndmask_b32_e32 v13, v13, v15, vcc
	v_sub_f32_e32 v13, v13, v14
	v_fma_f32 v14, v2, v12, v5
	v_cmp_gt_f32_e32 vcc, s30, v14
	v_add_f32_e32 v116, v13, v118
	v_mul_f32_e32 v13, 0xbfb8aa3b, v43
	v_cndmask_b32_e64 v15, 0, 32, vcc
	v_ldexp_f32 v14, v14, v15
	v_exp_f32_e32 v13, v13
	v_log_f32_e32 v14, v14
	v_rcp_f32_e32 v29, v16
	v_add_f32_e32 v13, 1.0, v13
	v_mul_f32_e32 v15, 0x3f317217, v14
	v_rcp_f32_e32 v13, v13
	v_fma_f32 v15, v14, s31, -v15
	v_fmac_f32_e32 v15, 0x3377d1cf, v14
	v_fmac_f32_e32 v15, 0x3f317217, v14
	v_cmp_lt_f32_e64 s[0:1], |v14|, s34
	s_nop 1
; template <bool DRY> DI void hgrn1_phase(LAS unsigned char* L, bf16* Z2, const float* lbraw, int layer, float* DEC, unsigned long long* OI, int G, int bid, int tid) {
;     ...
;         float run = 0.f;
; #pragma unroll
;         for (int r = 0; r < 16; ++r) { const float fl = cs[r]; const float sg = __builtin_amdgcn_rcpf(1.0f + __expf(-fl)); const float f = lbv + (1.0f - lbv) * sg;
;             kg[r] = (1.0f - lbv) * (1.0f - sg); run += __logf(f); cs[r] = run; }
;         TOT[rg * 128 + n] = run;
;         __syncthreads();
;         const float t0 = TOT[n], t1 = TOT[128 + n], t2 = TOT[256 + n], t3 = TOT[384 + n];
;         const float off = rg == 0 ? 0.f : (rg == 1 ? t0 : (rg == 2 ? t0 + t1 : t0 + t1 + t2));
	v_cndmask_b32_e64 v14, v14, v15, s[0:1]
	v_fma_f32 v15, v2, v13, v5
	v_cmp_gt_f32_e64 s[0:1], s30, v15
	s_nop 1
	v_cndmask_b32_e64 v21, 0, 32, s[0:1]
	v_ldexp_f32 v15, v15, v21
	v_cndmask_b32_e32 v21, 0, v243, vcc
	v_log_f32_e32 v15, v15
	v_sub_f32_e32 v14, v14, v21
	v_mul_f32_e32 v21, 0xbfb8aa3b, v103
	v_exp_f32_e32 v21, v21
	v_add_f32_e32 v115, v14, v116
	v_mul_f32_e32 v14, 0x3f317217, v15
	v_fma_f32 v24, v15, s31, -v14
	v_add_f32_e32 v14, 1.0, v21
	v_rcp_f32_e32 v14, v14
	v_fmac_f32_e32 v24, 0x3377d1cf, v15
	v_fmac_f32_e32 v24, 0x3f317217, v15
	v_cmp_lt_f32_e64 vcc, |v15|, s34
	v_cndmask_b32_e64 v21, 0, v243, s[0:1]
	s_nop 0
	v_cndmask_b32_e32 v15, v15, v24, vcc
	v_sub_f32_e32 v15, v15, v21
	v_fma_f32 v21, v2, v14, v5
	v_cmp_gt_f32_e32 vcc, s30, v21
	v_add_f32_e32 v113, v15, v115
	v_mul_f32_e32 v15, 0xbfb8aa3b, v104
	v_cndmask_b32_e64 v24, 0, 32, vcc
	v_ldexp_f32 v21, v21, v24
	v_exp_f32_e32 v15, v15
	v_log_f32_e32 v21, v21
	v_add_f32_e32 v15, 1.0, v15
	v_mul_f32_e32 v24, 0x3f317217, v21
	v_rcp_f32_e32 v15, v15
	v_fma_f32 v24, v21, s31, -v24
	v_fmac_f32_e32 v24, 0x3377d1cf, v21
	v_fmac_f32_e32 v24, 0x3f317217, v21
	v_cmp_lt_f32_e64 s[0:1], |v21|, s34
	s_nop 1
	v_cndmask_b32_e64 v21, v21, v24, s[0:1]
	v_fma_f32 v24, v2, v15, v5
	v_cmp_gt_f32_e64 s[0:1], s30, v24
	s_nop 1
	v_cndmask_b32_e64 v25, 0, 32, s[0:1]
	v_ldexp_f32 v24, v24, v25
	v_log_f32_e32 v25, v24
	v_cndmask_b32_e32 v24, 0, v243, vcc
	v_sub_f32_e32 v21, v21, v24
	v_mul_f32_e32 v24, 0xbfb8aa3b, v105
	v_exp_f32_e32 v24, v24
	v_add_f32_e32 v111, v21, v113
	v_mul_f32_e32 v21, 0x3f317217, v25
	v_fma_f32 v21, v25, s31, -v21
	v_add_f32_e32 v24, 1.0, v24
	v_rcp_f32_e32 v24, v24
	v_fmac_f32_e32 v21, 0x3377d1cf, v25
	v_fmac_f32_e32 v21, 0x3f317217, v25
	v_cmp_lt_f32_e64 vcc, |v25|, s34
	s_nop 1
	v_cndmask_b32_e32 v21, v25, v21, vcc
	v_cndmask_b32_e64 v25, 0, v243, s[0:1]
	v_sub_f32_e32 v21, v21, v25
	v_fma_f32 v25, v2, v24, v5
	v_cmp_gt_f32_e32 vcc, s30, v25
	v_add_f32_e32 v110, v21, v111
	s_nop 0
	v_cndmask_b32_e64 v26, 0, 32, vcc
	v_ldexp_f32 v25, v25, v26
	v_log_f32_e32 v26, v25
	v_rcp_f32_e32 v25, v20
	v_mul_f32_e32 v21, 0x3f317217, v26
	v_fma_f32 v21, v26, s31, -v21
	v_fmac_f32_e32 v21, 0x3377d1cf, v26
	v_fmac_f32_e32 v21, 0x3f317217, v26
	v_cmp_lt_f32_e64 s[0:1], |v26|, s34
	s_nop 1
	v_cndmask_b32_e64 v20, v26, v21, s[0:1]
	v_fma_f32 v21, v2, v25, v5
	v_cmp_gt_f32_e64 s[0:1], s30, v21
	s_nop 1
	v_cndmask_b32_e64 v26, 0, 32, s[0:1]
	v_ldexp_f32 v21, v21, v26
	v_log_f32_e32 v21, v21
	v_cndmask_b32_e32 v26, 0, v243, vcc
	v_sub_f32_e32 v20, v20, v26
	v_add_f32_e32 v108, v20, v110
	v_mul_f32_e32 v20, 0x3f317217, v21
	v_fma_f32 v20, v21, s31, -v20
	v_rcp_f32_e32 v26, v19
	v_fmac_f32_e32 v20, 0x3377d1cf, v21
	v_fmac_f32_e32 v20, 0x3f317217, v21
	v_cmp_lt_f32_e64 vcc, |v21|, s34
	s_nop 1
	v_cndmask_b32_e32 v19, v21, v20, vcc
	v_cndmask_b32_e64 v20, 0, v243, s[0:1]
	v_sub_f32_e32 v19, v19, v20
	v_fma_f32 v20, v2, v26, v5
	v_cmp_gt_f32_e32 vcc, s30, v20
	v_add_f32_e32 v106, v19, v108
	s_nop 0
	v_cndmask_b32_e64 v21, 0, 32, vcc
	v_ldexp_f32 v20, v20, v21
	v_log_f32_e32 v20, v20
	s_nop 0
	v_mul_f32_e32 v19, 0x3f317217, v20
	v_fma_f32 v19, v20, s31, -v19
	v_fmac_f32_e32 v19, 0x3377d1cf, v20
	v_fmac_f32_e32 v19, 0x3f317217, v20
	v_cmp_lt_f32_e64 s[0:1], |v20|, s34
	s_nop 1
	v_cndmask_b32_e64 v18, v20, v19, s[0:1]
	v_fma_f32 v19, v2, v27, v5
	v_cmp_gt_f32_e64 s[0:1], s30, v19
	s_nop 1
	v_cndmask_b32_e64 v20, 0, 32, s[0:1]
	v_ldexp_f32 v19, v19, v20
	v_log_f32_e32 v19, v19
	v_cndmask_b32_e32 v20, 0, v243, vcc
	v_sub_f32_e32 v18, v18, v20
	v_add_f32_e32 v105, v18, v106
	v_mul_f32_e32 v18, 0x3f317217, v19
	v_fma_f32 v18, v19, s31, -v18
	v_fmac_f32_e32 v18, 0x3377d1cf, v19
	v_fmac_f32_e32 v18, 0x3f317217, v19
	v_cmp_lt_f32_e64 vcc, |v19|, s34
	s_nop 1
	v_cndmask_b32_e32 v17, v19, v18, vcc
	v_cndmask_b32_e64 v18, 0, v243, s[0:1]
	v_sub_f32_e32 v17, v17, v18
	v_fma_f32 v18, v2, v28, v5
	v_cmp_gt_f32_e32 vcc, s30, v18
	v_add_f32_e32 v104, v17, v105
	v_fmac_f32_e32 v5, v2, v29
	v_cndmask_b32_e64 v19, 0, 32, vcc
	v_ldexp_f32 v18, v18, v19
	v_log_f32_e32 v18, v18
	s_nop 0
	v_mul_f32_e32 v17, 0x3f317217, v18
	v_fma_f32 v17, v18, s31, -v17
	v_fmac_f32_e32 v17, 0x3377d1cf, v18
	v_fmac_f32_e32 v17, 0x3f317217, v18
	v_cmp_lt_f32_e64 s[0:1], |v18|, s34
	s_nop 1
	v_cndmask_b32_e64 v16, v18, v17, s[0:1]
	v_cmp_gt_f32_e64 s[0:1], s30, v5
	s_nop 1
	v_cndmask_b32_e64 v17, 0, 32, s[0:1]
	v_ldexp_f32 v5, v5, v17
	v_log_f32_e32 v5, v5
	v_cndmask_b32_e32 v17, 0, v243, vcc
	v_sub_f32_e32 v16, v16, v17
	v_add_f32_e32 v103, v16, v104
	v_mul_f32_e32 v16, 0x3f317217, v5
	v_fma_f32 v16, v5, s31, -v16
	v_fmac_f32_e32 v16, 0x3377d1cf, v5
	v_fmac_f32_e32 v16, 0x3f317217, v5
	v_cmp_lt_f32_e64 vcc, |v5|, s34
	s_nop 1
	v_cndmask_b32_e32 v5, v5, v16, vcc
	v_cndmask_b32_e64 v16, 0, v243, s[0:1]
	v_sub_f32_e32 v5, v5, v16
	v_add_f32_e32 v5, v5, v103
	ds_write_b32 v44, v5 offset:53248
	s_waitcnt lgkmcnt(0)
	s_barrier
	ds_read2st64_b32 v[40:41], v45 offset0:208 offset1:210
	ds_read2st64_b32 v[42:43], v45 offset0:212 offset1:214
	s_and_saveexec_b64 s[0:1], s[38:39]
	s_cbranch_execz .LBB0_535
	v_cmp_lt_i32_e32 vcc, 1, v31
	s_mov_b64 s[30:31], 0
	s_and_saveexec_b64 s[34:35], vcc
	s_xor_b64 s[34:35], exec, s[34:35]
	s_cbranch_execz .LBB0_545
	v_cmp_eq_u32_e32 vcc, 2, v31
	s_mov_b64 s[30:31], -1
	s_and_saveexec_b64 s[50:51], vcc
	s_cbranch_execz .LBB0_531
	s_waitcnt lgkmcnt(1)
	v_add_f32_e32 v3, v40, v41
	s_xor_b64 s[30:31], exec, -1
